# attention phase only: per-MFMA s_setprio flips removed, one static s_setprio 1 for waves 4-7 (asymmetric arbitration so the two waves of a SIMD de-phase), GEMM flips kept
# baseline (speedup 1.0000x reference)
; #define LAS __attribute__((address_space(3)))
; __device__ __forceinline__ unsigned xb_add(unsigned* p, unsigned v) { return __hip_atomic_fetch_add(p, v, __ATOMIC_RELAXED, __HIP_MEMORY_SCOPE_AGENT); }
; __device__ __forceinline__ unsigned xb_xcc_id() { return (unsigned)__builtin_amdgcn_s_getreg((3 << 11) | 20) & 0xFu; }
; #define KWS() ((unsigned char*)karg_u64<136>())
; __device__ __forceinline__ XcdBarrier xcd_barrier_post(unsigned* bar, volatile LAS unsigned* st) {
;     XcdBarrier b; b.bar = bar; b.x = xb_xcc_id(); b.st = st;
;     if (threadIdx.x == 0) (void)xb_add(&bar[XB_XCNT(b.x)], 1u);
;     return b;
; __global__ void __launch_bounds__(NWAVES * 64, 2) fwd_kernel(Args args) {
;     extern __shared__ __attribute__((aligned(16))) unsigned char lds[];
;     LAS unsigned char* L = (LAS unsigned char*)lds;
;     const int G = gridDim.x, bx = blockIdx.x;
;     for (int u = threadIdx.x; u < (LDS_BYTES - LDSCTL_OFF) / 4; u += NWAVES * 64) ((LAS unsigned*)(L + LDSCTL_OFF))[u] = 0u;
;     __syncthreads();
;     XcdBarrier bar = xcd_barrier_post((unsigned*)(KWS() + WS_CTL) + CW_BAR, (volatile LAS unsigned*)(L + MISC_OFF) + 8);
_Z10fwd_kernel4Args:
	v_readfirstlane_b32 s101, v0
	s_nop 3
	s_and_b32 s101, s101, 0x3ff
	s_lshr_b32 s101, s101, 8
	s_load_dword s3, s[0:1], 0x90
	v_lshl_add_u32 v1, v0, 2, 0
	s_add_u32 s90, s0, 0x90
	v_add_u32_e32 v1, 0x20000, v1
	v_mov_b32_e32 v2, 0
	s_addc_u32 s91, s1, 0
	ds_write2st64_b32 v1, v2, v2 offset1:8
	ds_write2st64_b32 v1, v2, v2 offset0:16 offset1:24
	v_or_b32_e32 v1, 0x800, v0
	s_mov_b64 s[4:5], -1
	s_and_saveexec_b64 s[6:7], s[4:5]
	v_lshl_add_u32 v3, v1, 2, 0
	v_add_u32_e32 v3, 0x20000, v3
	ds_write_b32 v3, v2
	s_or_b64 exec, exec, s[6:7]
	s_and_saveexec_b64 s[6:7], s[4:5]
	s_add_i32 s4, 0, 0x20000
	v_lshl_add_u32 v1, v1, 2, s4
	v_mov_b32_e32 v2, 0
	ds_write_b32 v1, v2 offset:2048
	s_or_b64 exec, exec, s[6:7]
	v_or_b32_e32 v1, 0xc00, v0
	v_cmp_gt_u32_e64 s[4:5], 7, 6
	v_cmp_gt_u32_e64 s[8:9], 7, 5
	s_and_saveexec_b64 s[6:7], s[8:9]
	v_lshl_add_u32 v2, v1, 2, 0
	v_add_u32_e32 v2, 0x20000, v2
	v_mov_b32_e32 v3, 0
	ds_write_b32 v2, v3
	s_or_b64 exec, exec, s[6:7]
	s_and_saveexec_b64 s[6:7], s[4:5]
	s_add_i32 s4, 0, 0x20000
	v_lshl_add_u32 v1, v1, 2, s4
	v_mov_b32_e32 v2, 0
	ds_write_b32 v1, v2 offset:2048
	s_or_b64 exec, exec, s[6:7]
	s_waitcnt lgkmcnt(0)
	s_barrier
	s_load_dwordx2 s[4:5], s[0:1], 0x88
	s_waitcnt lgkmcnt(0)
	s_add_u32 s85, s4, 0x4000
	v_writelane_b32 v254, s4, 0
	s_addc_u32 s88, s5, 0
	v_cmp_eq_u32_e64 s[6:7], 0, v0
	v_writelane_b32 v254, s5, 1
	s_getreg_b32 s4, hwreg(HW_REG_XCC_ID, 0, 4)
	s_and_b32 s89, s4, 15
	s_mov_b64 s[4:5], exec
	v_writelane_b32 v254, s6, 2
	s_nop 1
	v_writelane_b32 v254, s7, 3
	s_and_b64 s[6:7], s[4:5], s[6:7]
	s_mov_b64 exec, s[6:7]
	s_cbranch_execz .LBB0_10
	s_lshl_b32 s6, s89, 8
	s_add_u32 s6, s85, s6
	s_addc_u32 s7, s88, 0
	v_mov_b32_e32 v1, 1
	v_mov_b64_e32 v[2:3], s[6:7]
	flat_atomic_add v[2:3], v1 offset:1024

; #define LAS __attribute__((address_space(3)))
; __global__ void __launch_bounds__(NWAVES * 64, 2) fwd_kernel(Args args) {
;     ...
;         for (int s = bx; s < 6 * 256; s += G) {
;             const int r = s >> 8, c = s & 255, xcd = c & 7, idx = c >> 3;
;             int b, kvh, h, qb, S_, row0;
;             if (r < 4) { const int grp = 4 * xcd + r; b = grp >> 2; kvh = grp & 3; h = kvh * 4 + (idx >> 3); qb = idx & 7; S_ = SEQ_P; row0 = b * SEQ_P; }
;             else { b = xcd >> 2; kvh = xcd & 3; const int un = idx + 32 * (r - 4); h = kvh * 4 + (un >> 4); qb = un & 15; S_ = SEQ_S; row0 = T_P + b * SEQ_S; }
;             att::attn_unit8(QB + (size_t)(row0 + qb * 256) * NQ + h * 128, ws + WS_K8 + (size_t)row0 * NKV + kvh * 128, ws + WS_VT8 + (size_t)((row0 >> 6) * 4 + kvh) * 8192,
;                             OB + (size_t)(row0 + qb * 256) * NQ + h * 128, S_, (LAS char*)(L + RING_OFF), qg, rope, qb * 256);
.LBB0_544:
	s_cmp_eq_u32 s101, 1
	s_cbranch_scc0 .Lattn_prio
	s_setprio 1

; __device__ __forceinline__ unsigned xb_ld(unsigned* p)              { return __hip_atomic_load(p, __ATOMIC_RELAXED, __HIP_MEMORY_SCOPE_AGENT); }
; __device__ __forceinline__ void xcd_barrier_complete(unsigned* bar, unsigned x, unsigned& nloc, unsigned& nx) {
;     const unsigned G = gridDim.x * gridDim.y * gridDim.z;
;     unsigned sum, cnt, mine, sp = 0u;
;     for (;;) {
;         sum = 0u; cnt = 0u; mine = 0u;
; #pragma unroll
;         for (unsigned j = 0; j < 16; ++j) { const unsigned c = xb_ld(&bar[XB_XCNT(j)]); sum += c; cnt += (c > 0u) ? 1u : 0u; mine = (j == x) ? c : mine; }
;         if (sum == G) break;
; __device__ __forceinline__ void xcd_barrier(const XcdBarrier& b) {
;     asm volatile("s_waitcnt vmcnt(0)" ::: "memory");
;     __syncthreads();
;     if (threadIdx.x == 0) {
;         unsigned* bar = b.bar;
;         __builtin_amdgcn_s_waitcnt(0);
;         unsigned nloc = b.st[0], nx = b.st[1];
;         if (nloc == 0u) { xcd_barrier_complete(bar, b.x, nloc, nx); b.st[0] = nloc; b.st[1] = nx; }
.LBB0_567:
	s_setprio 0
	s_waitcnt vmcnt(0)
	s_barrier
	s_mov_b64 s[40:41], exec
	v_readlane_b32 s4, v254, 2
	v_readlane_b32 s5, v254, 3
	s_and_b64 s[4:5], s[40:41], s[4:5]
	s_mov_b64 exec, s[4:5]
	s_cbranch_execz .LBB0_611
	s_add_i32 s4, 0, 0x20160
	v_mov_b32_e32 v2, s4
	s_waitcnt vmcnt(0) expcnt(0) lgkmcnt(0)
	ds_read_b32 v4, v2
	s_add_i32 s4, 0, 0x20164
	v_mov_b32_e32 v2, s4
	ds_read_b32 v2, v2
	s_waitcnt lgkmcnt(1)
	v_cmp_ne_u32_e32 vcc, 0, v4
	s_cbranch_vccnz .LBB0_582
	v_readlane_b32 s8, v254, 0
	v_readlane_b32 s9, v254, 1
	s_add_u32 s6, s8, 0x4200
	s_addc_u32 s7, s9, 0
	s_add_u32 s10, s8, 0x4400
	s_addc_u32 s11, s9, 0
	s_add_u32 s12, s8, 0x4500
	s_addc_u32 s13, s9, 0
	s_add_u32 s14, s8, 0x4600
	s_addc_u32 s15, s9, 0
	s_add_u32 s16, s8, 0x4700
	s_addc_u32 s17, s9, 0
	s_add_u32 s18, s8, 0x4800
	s_addc_u32 s19, s9, 0
	s_add_u32 s20, s8, 0x4900
	s_addc_u32 s21, s9, 0
	s_add_u32 s22, s8, 0x4a00
	s_addc_u32 s23, s9, 0
	s_add_u32 s24, s8, 0x4b00
	s_addc_u32 s25, s9, 0
	s_add_u32 s26, s8, 0x4c00
	s_addc_u32 s27, s9, 0
	s_add_u32 s28, s8, 0x4d00
	s_addc_u32 s29, s9, 0
	s_add_u32 s30, s8, 0x4e00
	s_addc_u32 s31, s9, 0
	s_add_u32 s34, s8, 0x4f00
	s_addc_u32 s35, s9, 0
	s_add_u32 s36, s8, 0x5000
	s_addc_u32 s37, s9, 0
	s_load_dwordx2 s[4:5], s[90:91], 0x4
	s_add_u32 s38, s8, 0x5100
	s_addc_u32 s39, s9, 0
	s_add_u32 s42, s8, 0x5200
	s_addc_u32 s43, s9, 0
	s_add_u32 s44, s8, 0x5300
	s_waitcnt lgkmcnt(0)
	s_mul_i32 s4, s4, s3
	s_addc_u32 s45, s9, 0
	s_mul_i32 s4, s4, s5
	s_mov_b32 s5, 1
	s_mov_b64 s[8:9], 0
	v_mov_b64_e32 v[2:3], s[10:11]
	v_mov_b64_e32 v[4:5], s[12:13]
	v_mov_b64_e32 v[6:7], s[14:15]
	v_mov_b64_e32 v[8:9], s[16:17]
	v_mov_b64_e32 v[10:11], s[18:19]
	v_mov_b64_e32 v[12:13], s[20:21]
	v_mov_b64_e32 v[14:15], s[22:23]
	v_mov_b64_e32 v[16:17], s[24:25]
	v_mov_b64_e32 v[18:19], s[26:27]
	v_mov_b64_e32 v[20:21], s[28:29]
	v_mov_b64_e32 v[22:23], s[30:31]
	v_mov_b64_e32 v[24:25], s[34:35]
	v_mov_b64_e32 v[26:27], s[36:37]
	v_mov_b64_e32 v[28:29], s[38:39]
	v_mov_b64_e32 v[30:31], s[42:43]
	v_mov_b64_e32 v[32:33], s[44:45]
	s_branch .LBB0_572
